# attention loops without any s_setprio (priority raise removed from the MFMA halves)
# baseline (speedup 1.0000x reference)
.Lwd_b1:
	s_barrier
	ds_read_b64_tr_b16 v[96:97], v205 offset:34816
	ds_read_b64_tr_b16 v[98:99], v205 offset:37376
	ds_read_b64_tr_b16 v[100:101], v205 offset:39936
	ds_read_b64_tr_b16 v[102:103], v205 offset:42496
	ds_read_b64_tr_b16 v[104:105], v205 offset:45056
	ds_read_b64_tr_b16 v[106:107], v205 offset:47616
	ds_read_b64_tr_b16 v[108:109], v205 offset:50176
	ds_read_b64_tr_b16 v[110:111], v205 offset:52736
	ds_read_b64_tr_b16 v[176:177], v205 offset:34880
	ds_read_b64_tr_b16 v[178:179], v205 offset:37440
	ds_read_b64_tr_b16 v[180:181], v205 offset:40000
	ds_read_b64_tr_b16 v[182:183], v205 offset:42560
	ds_read_b64_tr_b16 v[184:185], v205 offset:45120
	ds_read_b64_tr_b16 v[186:187], v205 offset:47680
	s_waitcnt lgkmcnt(12)
	v_mfma_f32_32x32x16_bf16 v[32:47], v[96:99], v[80:83], v[32:47]
	ds_read_b64_tr_b16 v[96:97], v205 offset:50240
	ds_read_b64_tr_b16 v[98:99], v205 offset:52800
	s_waitcnt lgkmcnt(12)
	v_mfma_f32_32x32x16_bf16 v[32:47], v[100:103], v[84:87], v[32:47]
	ds_read_b64_tr_b16 v[100:101], v205 offset:34944
	ds_read_b64_tr_b16 v[102:103], v205 offset:37504
	s_waitcnt lgkmcnt(12)
	v_mfma_f32_32x32x16_bf16 v[32:47], v[104:107], v[88:91], v[32:47]
	ds_read_b64_tr_b16 v[104:105], v205 offset:40064
	ds_read_b64_tr_b16 v[106:107], v205 offset:42624
	s_waitcnt lgkmcnt(12)
	v_mfma_f32_32x32x16_bf16 v[32:47], v[108:111], v[92:95], v[32:47]
	ds_read_b64_tr_b16 v[108:109], v205 offset:45184
	ds_read_b64_tr_b16 v[110:111], v205 offset:47744
	s_waitcnt lgkmcnt(12)
	v_mfma_f32_32x32x16_bf16 v[16:31], v[176:179], v[80:83], v[16:31]
	ds_read_b64_tr_b16 v[176:177], v205 offset:50304
	ds_read_b64_tr_b16 v[178:179], v205 offset:52864
	s_waitcnt lgkmcnt(12)
	v_mfma_f32_32x32x16_bf16 v[16:31], v[180:183], v[84:87], v[16:31]
	ds_read_b64_tr_b16 v[180:181], v205 offset:35008
	ds_read_b64_tr_b16 v[182:183], v205 offset:37568
	s_waitcnt lgkmcnt(12)
	v_mfma_f32_32x32x16_bf16 v[16:31], v[184:187], v[88:91], v[16:31]
	ds_read_b64_tr_b16 v[184:185], v205 offset:40128
	ds_read_b64_tr_b16 v[186:187], v205 offset:42688
	s_waitcnt lgkmcnt(12)
	v_mfma_f32_32x32x16_bf16 v[16:31], v[96:99], v[92:95], v[16:31]
	ds_read_b64_tr_b16 v[96:97], v205 offset:45248
	ds_read_b64_tr_b16 v[98:99], v205 offset:47808
	s_waitcnt lgkmcnt(12)
	v_mfma_f32_32x32x16_bf16 v[0:15], v[100:103], v[80:83], v[0:15]
	ds_read_b64_tr_b16 v[100:101], v205 offset:50368
	ds_read_b64_tr_b16 v[102:103], v205 offset:52928
	s_waitcnt lgkmcnt(12)
	v_mfma_f32_32x32x16_bf16 v[0:15], v[104:107], v[84:87], v[0:15]
	ds_read_b128 v[210:213], v206 offset:8704
	ds_read_b128 v[104:107], v206 offset:8736
	s_waitcnt lgkmcnt(12)
	v_mfma_f32_32x32x16_bf16 v[0:15], v[108:111], v[88:91], v[0:15]
	ds_read_b128 v[108:111], v206 offset:8768
	ds_read_b128 v[188:191], v206
	s_waitcnt lgkmcnt(12)
	v_mfma_f32_32x32x16_bf16 v[0:15], v[176:179], v[92:95], v[0:15]
	ds_read_b128 v[176:179], v206 offset:8800
	ds_read_b128 v[224:227], v206 offset:32
	s_waitcnt lgkmcnt(12)
	v_mfma_f32_32x32x16_bf16 v[48:63], v[180:183], v[80:83], v[48:63]
	ds_read_b128 v[228:231], v206 offset:64
	ds_read_b128 v[248:251], v206 offset:96
	s_waitcnt lgkmcnt(12)
	v_mfma_f32_32x32x16_bf16 v[48:63], v[184:187], v[84:87], v[48:63]
	s_waitcnt lgkmcnt(10)
	v_mfma_f32_32x32x16_bf16 v[48:63], v[96:99], v[88:91], v[48:63]
	s_waitcnt lgkmcnt(8)
	v_mfma_f32_32x32x16_bf16 v[48:63], v[100:103], v[92:95], v[48:63]
	s_waitcnt lgkmcnt(7)
	v_mfma_f32_32x32x16_bf16 v[80:95], v[210:213], v[112:115], v[64:79]
	s_waitcnt lgkmcnt(6)
	v_mfma_f32_32x32x16_bf16 v[80:95], v[104:107], v[116:119], v[80:95]
	s_waitcnt lgkmcnt(5)
	v_mfma_f32_32x32x16_bf16 v[80:95], v[108:111], v[120:123], v[80:95]
	s_waitcnt lgkmcnt(3)
	v_mfma_f32_32x32x16_bf16 v[80:95], v[176:179], v[124:127], v[80:95]
	s_waitcnt lgkmcnt(4)
	v_mfma_f32_32x32x16_bf16 v[96:111], v[188:191], v[112:115], v[64:79]
	s_waitcnt lgkmcnt(2)
	v_mfma_f32_32x32x16_bf16 v[96:111], v[224:227], v[116:119], v[96:111]
	s_waitcnt lgkmcnt(1)
	v_mfma_f32_32x32x16_bf16 v[96:111], v[228:231], v[120:123], v[96:111]
	s_waitcnt lgkmcnt(0)
	v_mfma_f32_32x32x16_bf16 v[96:111], v[248:251], v[124:127], v[96:111]
	s_cmp_gt_i32 s33, 3
	s_cbranch_scc0 .Lbn_b1

.LA1_top:
	v_add_u32_e32 v205, 0x0, v165
	v_add_u32_e32 v206, 0x4400, v192
	ds_read_b64_tr_b16 v[96:97], v205 offset:34816
	ds_read_b64_tr_b16 v[98:99], v205 offset:37376
	ds_read_b64_tr_b16 v[100:101], v205 offset:39936
	ds_read_b64_tr_b16 v[102:103], v205 offset:42496
	ds_read_b64_tr_b16 v[104:105], v205 offset:45056
	ds_read_b64_tr_b16 v[106:107], v205 offset:47616
	ds_read_b64_tr_b16 v[108:109], v205 offset:50176
	ds_read_b64_tr_b16 v[110:111], v205 offset:52736
	ds_read_b64_tr_b16 v[176:177], v205 offset:34880
	ds_read_b64_tr_b16 v[178:179], v205 offset:37440
	ds_read_b64_tr_b16 v[180:181], v205 offset:40000
	ds_read_b64_tr_b16 v[182:183], v205 offset:42560
	ds_read_b64_tr_b16 v[184:185], v205 offset:45120
	ds_read_b64_tr_b16 v[186:187], v205 offset:47680
	s_waitcnt lgkmcnt(12)
	v_mfma_f32_32x32x16_bf16 v[32:47], v[96:99], v[80:83], v[32:47]
	ds_read_b64_tr_b16 v[96:97], v205 offset:50240
	ds_read_b64_tr_b16 v[98:99], v205 offset:52800
	s_waitcnt lgkmcnt(12)
	v_mfma_f32_32x32x16_bf16 v[32:47], v[100:103], v[84:87], v[32:47]
	ds_read_b64_tr_b16 v[100:101], v205 offset:34944
	ds_read_b64_tr_b16 v[102:103], v205 offset:37504
	s_waitcnt lgkmcnt(12)
	v_mfma_f32_32x32x16_bf16 v[32:47], v[104:107], v[88:91], v[32:47]
	ds_read_b64_tr_b16 v[104:105], v205 offset:40064
	ds_read_b64_tr_b16 v[106:107], v205 offset:42624
	s_waitcnt lgkmcnt(12)
	v_mfma_f32_32x32x16_bf16 v[32:47], v[108:111], v[92:95], v[32:47]
	ds_read_b64_tr_b16 v[108:109], v205 offset:45184
	ds_read_b64_tr_b16 v[110:111], v205 offset:47744
	s_waitcnt lgkmcnt(12)
	v_mfma_f32_32x32x16_bf16 v[16:31], v[176:179], v[80:83], v[16:31]
	ds_read_b64_tr_b16 v[176:177], v205 offset:50304
	ds_read_b64_tr_b16 v[178:179], v205 offset:52864
	s_waitcnt lgkmcnt(12)
	v_mfma_f32_32x32x16_bf16 v[16:31], v[180:183], v[84:87], v[16:31]
	ds_read_b64_tr_b16 v[180:181], v205 offset:35008
	ds_read_b64_tr_b16 v[182:183], v205 offset:37568
	s_waitcnt lgkmcnt(12)
	v_mfma_f32_32x32x16_bf16 v[16:31], v[184:187], v[88:91], v[16:31]
	ds_read_b64_tr_b16 v[184:185], v205 offset:40128
	ds_read_b64_tr_b16 v[186:187], v205 offset:42688
	s_waitcnt lgkmcnt(12)
	v_mfma_f32_32x32x16_bf16 v[16:31], v[96:99], v[92:95], v[16:31]
	ds_read_b64_tr_b16 v[96:97], v205 offset:45248
	ds_read_b64_tr_b16 v[98:99], v205 offset:47808
	s_waitcnt lgkmcnt(12)
	v_mfma_f32_32x32x16_bf16 v[0:15], v[100:103], v[80:83], v[0:15]
	ds_read_b64_tr_b16 v[100:101], v205 offset:50368
	ds_read_b64_tr_b16 v[102:103], v205 offset:52928
	s_waitcnt lgkmcnt(12)
	v_mfma_f32_32x32x16_bf16 v[0:15], v[104:107], v[84:87], v[0:15]
	ds_read_b128 v[210:213], v206 offset:8704
	ds_read_b128 v[104:107], v206 offset:8736
	s_waitcnt lgkmcnt(12)
	v_mfma_f32_32x32x16_bf16 v[0:15], v[108:111], v[88:91], v[0:15]
	ds_read_b128 v[108:111], v206 offset:8768
	ds_read_b128 v[188:191], v206
	s_waitcnt lgkmcnt(12)
	v_mfma_f32_32x32x16_bf16 v[0:15], v[176:179], v[92:95], v[0:15]
	ds_read_b128 v[176:179], v206 offset:8800
	ds_read_b128 v[224:227], v206 offset:32
	s_waitcnt lgkmcnt(12)
	v_mfma_f32_32x32x16_bf16 v[48:63], v[180:183], v[80:83], v[48:63]
	ds_read_b128 v[228:231], v206 offset:64
	ds_read_b128 v[248:251], v206 offset:96
	s_waitcnt lgkmcnt(12)
	v_mfma_f32_32x32x16_bf16 v[48:63], v[184:187], v[84:87], v[48:63]
	s_waitcnt lgkmcnt(10)
	v_mfma_f32_32x32x16_bf16 v[48:63], v[96:99], v[88:91], v[48:63]
	s_waitcnt lgkmcnt(8)
	v_mfma_f32_32x32x16_bf16 v[48:63], v[100:103], v[92:95], v[48:63]
	s_waitcnt lgkmcnt(7)
	v_mfma_f32_32x32x16_bf16 v[80:95], v[210:213], v[112:115], v[64:79]
	s_waitcnt lgkmcnt(6)
	v_mfma_f32_32x32x16_bf16 v[80:95], v[104:107], v[116:119], v[80:95]
	s_waitcnt lgkmcnt(5)
	v_mfma_f32_32x32x16_bf16 v[80:95], v[108:111], v[120:123], v[80:95]
	s_waitcnt lgkmcnt(3)
	v_mfma_f32_32x32x16_bf16 v[80:95], v[176:179], v[124:127], v[80:95]
	s_waitcnt lgkmcnt(4)
	v_mfma_f32_32x32x16_bf16 v[96:111], v[188:191], v[112:115], v[64:79]
	s_waitcnt lgkmcnt(2)
	v_mfma_f32_32x32x16_bf16 v[96:111], v[224:227], v[116:119], v[96:111]
	s_waitcnt lgkmcnt(1)
	v_mfma_f32_32x32x16_bf16 v[96:111], v[228:231], v[120:123], v[96:111]
	s_waitcnt lgkmcnt(0)
	v_mfma_f32_32x32x16_bf16 v[96:111], v[248:251], v[124:127], v[96:111]
	s_cmp_gt_i32 s33, 2
	s_cbranch_scc0 .Lba_a1

.LA2_top:
	v_add_u32_e32 v205, 0x5000, v165
	v_add_u32_e32 v206, 0x20400, v192
	ds_read_b64_tr_b16 v[96:97], v205 offset:34816
	ds_read_b64_tr_b16 v[98:99], v205 offset:37376
	ds_read_b64_tr_b16 v[100:101], v205 offset:39936
	ds_read_b64_tr_b16 v[102:103], v205 offset:42496
	ds_read_b64_tr_b16 v[104:105], v205 offset:45056
	ds_read_b64_tr_b16 v[106:107], v205 offset:47616
	ds_read_b64_tr_b16 v[108:109], v205 offset:50176
	ds_read_b64_tr_b16 v[110:111], v205 offset:52736
	ds_read_b64_tr_b16 v[176:177], v205 offset:34880
	ds_read_b64_tr_b16 v[178:179], v205 offset:37440
	ds_read_b64_tr_b16 v[180:181], v205 offset:40000
	ds_read_b64_tr_b16 v[182:183], v205 offset:42560
	ds_read_b64_tr_b16 v[184:185], v205 offset:45120
	ds_read_b64_tr_b16 v[186:187], v205 offset:47680
	s_waitcnt lgkmcnt(12)
	v_mfma_f32_32x32x16_bf16 v[32:47], v[96:99], v[80:83], v[32:47]
	ds_read_b64_tr_b16 v[96:97], v205 offset:50240
	ds_read_b64_tr_b16 v[98:99], v205 offset:52800
	s_waitcnt lgkmcnt(12)
	v_mfma_f32_32x32x16_bf16 v[32:47], v[100:103], v[84:87], v[32:47]
	ds_read_b64_tr_b16 v[100:101], v205 offset:34944
	ds_read_b64_tr_b16 v[102:103], v205 offset:37504
	s_waitcnt lgkmcnt(12)
	v_mfma_f32_32x32x16_bf16 v[32:47], v[104:107], v[88:91], v[32:47]
	ds_read_b64_tr_b16 v[104:105], v205 offset:40064
	ds_read_b64_tr_b16 v[106:107], v205 offset:42624
	s_waitcnt lgkmcnt(12)
	v_mfma_f32_32x32x16_bf16 v[32:47], v[108:111], v[92:95], v[32:47]
	ds_read_b64_tr_b16 v[108:109], v205 offset:45184
	ds_read_b64_tr_b16 v[110:111], v205 offset:47744
	s_waitcnt lgkmcnt(12)
	v_mfma_f32_32x32x16_bf16 v[16:31], v[176:179], v[80:83], v[16:31]
	ds_read_b64_tr_b16 v[176:177], v205 offset:50304
	ds_read_b64_tr_b16 v[178:179], v205 offset:52864
	s_waitcnt lgkmcnt(12)
	v_mfma_f32_32x32x16_bf16 v[16:31], v[180:183], v[84:87], v[16:31]
	ds_read_b64_tr_b16 v[180:181], v205 offset:35008
	ds_read_b64_tr_b16 v[182:183], v205 offset:37568
	s_waitcnt lgkmcnt(12)
	v_mfma_f32_32x32x16_bf16 v[16:31], v[184:187], v[88:91], v[16:31]
	ds_read_b64_tr_b16 v[184:185], v205 offset:40128
	ds_read_b64_tr_b16 v[186:187], v205 offset:42688
	s_waitcnt lgkmcnt(12)
	v_mfma_f32_32x32x16_bf16 v[16:31], v[96:99], v[92:95], v[16:31]
	ds_read_b64_tr_b16 v[96:97], v205 offset:45248
	ds_read_b64_tr_b16 v[98:99], v205 offset:47808
	s_waitcnt lgkmcnt(12)
	v_mfma_f32_32x32x16_bf16 v[0:15], v[100:103], v[80:83], v[0:15]
	ds_read_b64_tr_b16 v[100:101], v205 offset:50368
	ds_read_b64_tr_b16 v[102:103], v205 offset:52928
	s_waitcnt lgkmcnt(12)
	v_mfma_f32_32x32x16_bf16 v[0:15], v[104:107], v[84:87], v[0:15]
	ds_read_b128 v[210:213], v206 offset:8704
	ds_read_b128 v[104:107], v206 offset:8736
	s_waitcnt lgkmcnt(12)
	v_mfma_f32_32x32x16_bf16 v[0:15], v[108:111], v[88:91], v[0:15]
	ds_read_b128 v[108:111], v206 offset:8768
	ds_read_b128 v[188:191], v206
	s_waitcnt lgkmcnt(12)
	v_mfma_f32_32x32x16_bf16 v[0:15], v[176:179], v[92:95], v[0:15]
	ds_read_b128 v[176:179], v206 offset:8800
	ds_read_b128 v[224:227], v206 offset:32
	s_waitcnt lgkmcnt(12)
	v_mfma_f32_32x32x16_bf16 v[48:63], v[180:183], v[80:83], v[48:63]
	ds_read_b128 v[228:231], v206 offset:64
	ds_read_b128 v[248:251], v206 offset:96
	s_waitcnt lgkmcnt(12)
	v_mfma_f32_32x32x16_bf16 v[48:63], v[184:187], v[84:87], v[48:63]
	s_waitcnt lgkmcnt(10)
	v_mfma_f32_32x32x16_bf16 v[48:63], v[96:99], v[88:91], v[48:63]
	s_waitcnt lgkmcnt(8)
	v_mfma_f32_32x32x16_bf16 v[48:63], v[100:103], v[92:95], v[48:63]
	s_waitcnt lgkmcnt(7)
	v_mfma_f32_32x32x16_bf16 v[80:95], v[210:213], v[112:115], v[64:79]
	s_waitcnt lgkmcnt(6)
	v_mfma_f32_32x32x16_bf16 v[80:95], v[104:107], v[116:119], v[80:95]
	s_waitcnt lgkmcnt(5)
	v_mfma_f32_32x32x16_bf16 v[80:95], v[108:111], v[120:123], v[80:95]
	s_waitcnt lgkmcnt(3)
	v_mfma_f32_32x32x16_bf16 v[80:95], v[176:179], v[124:127], v[80:95]
	s_waitcnt lgkmcnt(4)
	v_mfma_f32_32x32x16_bf16 v[96:111], v[188:191], v[112:115], v[64:79]
	s_waitcnt lgkmcnt(2)
	v_mfma_f32_32x32x16_bf16 v[96:111], v[224:227], v[116:119], v[96:111]
	s_waitcnt lgkmcnt(1)
	v_mfma_f32_32x32x16_bf16 v[96:111], v[228:231], v[120:123], v[96:111]
	s_waitcnt lgkmcnt(0)
	v_mfma_f32_32x32x16_bf16 v[96:111], v[248:251], v[124:127], v[96:111]
	s_cmp_gt_i32 s33, 2
	s_cbranch_scc0 .Lba_a2

.LA0_top:
	v_add_u32_e32 v205, 0xa000, v165
	v_add_u32_e32 v206, 0x0, v192
	ds_read_b64_tr_b16 v[96:97], v205 offset:34816
	ds_read_b64_tr_b16 v[98:99], v205 offset:37376
	ds_read_b64_tr_b16 v[100:101], v205 offset:39936
	ds_read_b64_tr_b16 v[102:103], v205 offset:42496
	ds_read_b64_tr_b16 v[104:105], v205 offset:45056
	ds_read_b64_tr_b16 v[106:107], v205 offset:47616
	ds_read_b64_tr_b16 v[108:109], v205 offset:50176
	ds_read_b64_tr_b16 v[110:111], v205 offset:52736
	ds_read_b64_tr_b16 v[176:177], v205 offset:34880
	ds_read_b64_tr_b16 v[178:179], v205 offset:37440
	ds_read_b64_tr_b16 v[180:181], v205 offset:40000
	ds_read_b64_tr_b16 v[182:183], v205 offset:42560
	ds_read_b64_tr_b16 v[184:185], v205 offset:45120
	ds_read_b64_tr_b16 v[186:187], v205 offset:47680
	s_waitcnt lgkmcnt(12)
	v_mfma_f32_32x32x16_bf16 v[32:47], v[96:99], v[80:83], v[32:47]
	ds_read_b64_tr_b16 v[96:97], v205 offset:50240
	ds_read_b64_tr_b16 v[98:99], v205 offset:52800
	s_waitcnt lgkmcnt(12)
	v_mfma_f32_32x32x16_bf16 v[32:47], v[100:103], v[84:87], v[32:47]
	ds_read_b64_tr_b16 v[100:101], v205 offset:34944
	ds_read_b64_tr_b16 v[102:103], v205 offset:37504
	s_waitcnt lgkmcnt(12)
	v_mfma_f32_32x32x16_bf16 v[32:47], v[104:107], v[88:91], v[32:47]
	ds_read_b64_tr_b16 v[104:105], v205 offset:40064
	ds_read_b64_tr_b16 v[106:107], v205 offset:42624
	s_waitcnt lgkmcnt(12)
	v_mfma_f32_32x32x16_bf16 v[32:47], v[108:111], v[92:95], v[32:47]
	ds_read_b64_tr_b16 v[108:109], v205 offset:45184
	ds_read_b64_tr_b16 v[110:111], v205 offset:47744
	s_waitcnt lgkmcnt(12)
	v_mfma_f32_32x32x16_bf16 v[16:31], v[176:179], v[80:83], v[16:31]
	ds_read_b64_tr_b16 v[176:177], v205 offset:50304
	ds_read_b64_tr_b16 v[178:179], v205 offset:52864
	s_waitcnt lgkmcnt(12)
	v_mfma_f32_32x32x16_bf16 v[16:31], v[180:183], v[84:87], v[16:31]
	ds_read_b64_tr_b16 v[180:181], v205 offset:35008
	ds_read_b64_tr_b16 v[182:183], v205 offset:37568
	s_waitcnt lgkmcnt(12)
	v_mfma_f32_32x32x16_bf16 v[16:31], v[184:187], v[88:91], v[16:31]
	ds_read_b64_tr_b16 v[184:185], v205 offset:40128
	ds_read_b64_tr_b16 v[186:187], v205 offset:42688
	s_waitcnt lgkmcnt(12)
	v_mfma_f32_32x32x16_bf16 v[16:31], v[96:99], v[92:95], v[16:31]
	ds_read_b64_tr_b16 v[96:97], v205 offset:45248
	ds_read_b64_tr_b16 v[98:99], v205 offset:47808
	s_waitcnt lgkmcnt(12)
	v_mfma_f32_32x32x16_bf16 v[0:15], v[100:103], v[80:83], v[0:15]
	ds_read_b64_tr_b16 v[100:101], v205 offset:50368
	ds_read_b64_tr_b16 v[102:103], v205 offset:52928
	s_waitcnt lgkmcnt(12)
	v_mfma_f32_32x32x16_bf16 v[0:15], v[104:107], v[84:87], v[0:15]
	ds_read_b128 v[210:213], v206 offset:8704
	ds_read_b128 v[104:107], v206 offset:8736
	s_waitcnt lgkmcnt(12)
	v_mfma_f32_32x32x16_bf16 v[0:15], v[108:111], v[88:91], v[0:15]
	ds_read_b128 v[108:111], v206 offset:8768
	ds_read_b128 v[188:191], v206
	s_waitcnt lgkmcnt(12)
	v_mfma_f32_32x32x16_bf16 v[0:15], v[176:179], v[92:95], v[0:15]
	ds_read_b128 v[176:179], v206 offset:8800
	ds_read_b128 v[224:227], v206 offset:32
	s_waitcnt lgkmcnt(12)
	v_mfma_f32_32x32x16_bf16 v[48:63], v[180:183], v[80:83], v[48:63]
	ds_read_b128 v[228:231], v206 offset:64
	ds_read_b128 v[248:251], v206 offset:96
	s_waitcnt lgkmcnt(12)
	v_mfma_f32_32x32x16_bf16 v[48:63], v[184:187], v[84:87], v[48:63]
	s_waitcnt lgkmcnt(10)
	v_mfma_f32_32x32x16_bf16 v[48:63], v[96:99], v[88:91], v[48:63]
	s_waitcnt lgkmcnt(8)
	v_mfma_f32_32x32x16_bf16 v[48:63], v[100:103], v[92:95], v[48:63]
	s_waitcnt lgkmcnt(7)
	v_mfma_f32_32x32x16_bf16 v[80:95], v[210:213], v[112:115], v[64:79]
	s_waitcnt lgkmcnt(6)
	v_mfma_f32_32x32x16_bf16 v[80:95], v[104:107], v[116:119], v[80:95]
	s_waitcnt lgkmcnt(5)
	v_mfma_f32_32x32x16_bf16 v[80:95], v[108:111], v[120:123], v[80:95]
	s_waitcnt lgkmcnt(3)
	v_mfma_f32_32x32x16_bf16 v[80:95], v[176:179], v[124:127], v[80:95]
	s_waitcnt lgkmcnt(4)
	v_mfma_f32_32x32x16_bf16 v[96:111], v[188:191], v[112:115], v[64:79]
	s_waitcnt lgkmcnt(2)
	v_mfma_f32_32x32x16_bf16 v[96:111], v[224:227], v[116:119], v[96:111]
	s_waitcnt lgkmcnt(1)
	v_mfma_f32_32x32x16_bf16 v[96:111], v[228:231], v[120:123], v[96:111]
	s_waitcnt lgkmcnt(0)
	v_mfma_f32_32x32x16_bf16 v[96:111], v[248:251], v[124:127], v[96:111]
	s_cmp_gt_i32 s33, 2
	s_cbranch_scc0 .Lba_a0
